# v6 + accumulator zeroing with v_mov_b64 (64 instead of 128 moves per unit) in all 8 GEMM loops
# speedup vs baseline: 1.0057x; 1.0013x over previous
.LBB0_133:
	s_ashr_i32 s17, s16, 31
	s_lshl_b64 s[12:13], s[16:17], 21
	s_add_u32 s18, s25, s12
	s_addc_u32 s19, s26, s13
	s_and_b64 s[12:13], s[2:3], exec
	s_cselect_b32 s12, s19, s35
	s_cselect_b32 s13, s18, s34
	s_ashr_i32 s15, s14, 31
	s_lshl_b64 s[20:21], s[14:15], 21
	s_add_u32 s20, s27, s20
	s_addc_u32 s21, s40, s21
	s_and_b64 s[38:39], s[2:3], exec
	s_cselect_b32 s15, s21, s37
	s_cselect_b32 s57, s20, s36
	s_add_u32 s34, s34, 0x100080
	s_addc_u32 s35, s35, 0
	s_add_u32 s58, s36, 0x100
	v_mov_b32_e32 v0, 0
	s_addc_u32 s59, s37, 0
	s_mov_b32 s60, -2
	v_mov_b64_e32 v[0:1], 0
	v_mov_b64_e32 v[2:3], 0
	v_mov_b64_e32 v[4:5], 0
	v_mov_b64_e32 v[6:7], 0
	v_mov_b64_e32 v[8:9], 0
	v_mov_b64_e32 v[10:11], 0
	v_mov_b64_e32 v[12:13], 0
	v_mov_b64_e32 v[14:15], 0
	v_mov_b64_e32 v[16:17], 0
	v_mov_b64_e32 v[18:19], 0
	v_mov_b64_e32 v[20:21], 0
	v_mov_b64_e32 v[22:23], 0
	v_mov_b64_e32 v[24:25], 0
	v_mov_b64_e32 v[26:27], 0
	v_mov_b64_e32 v[28:29], 0
	v_mov_b64_e32 v[30:31], 0
	v_mov_b64_e32 v[32:33], 0
	v_mov_b64_e32 v[34:35], 0
	v_mov_b64_e32 v[36:37], 0
	v_mov_b64_e32 v[38:39], 0
	v_mov_b64_e32 v[40:41], 0
	v_mov_b64_e32 v[42:43], 0
	v_mov_b64_e32 v[44:45], 0
	v_mov_b64_e32 v[46:47], 0
	v_mov_b64_e32 v[48:49], 0
	v_mov_b64_e32 v[50:51], 0
	v_mov_b64_e32 v[52:53], 0
	v_mov_b64_e32 v[54:55], 0
	v_mov_b64_e32 v[56:57], 0
	v_mov_b64_e32 v[58:59], 0
	v_mov_b64_e32 v[60:61], 0
	v_mov_b64_e32 v[62:63], 0
	v_mov_b64_e32 v[64:65], 0
	v_mov_b64_e32 v[66:67], 0
	v_mov_b64_e32 v[68:69], 0
	v_mov_b64_e32 v[70:71], 0
	v_mov_b64_e32 v[72:73], 0
	v_mov_b64_e32 v[74:75], 0
	v_mov_b64_e32 v[76:77], 0
	v_mov_b64_e32 v[78:79], 0
	v_mov_b64_e32 v[80:81], 0
	v_mov_b64_e32 v[82:83], 0
	v_mov_b64_e32 v[84:85], 0
	v_mov_b64_e32 v[86:87], 0
	v_mov_b64_e32 v[88:89], 0
	v_mov_b64_e32 v[90:91], 0
	v_mov_b64_e32 v[92:93], 0
	v_mov_b64_e32 v[94:95], 0
	v_mov_b64_e32 v[96:97], 0
	v_mov_b64_e32 v[98:99], 0
	v_mov_b64_e32 v[100:101], 0
	v_mov_b64_e32 v[102:103], 0
	v_mov_b64_e32 v[104:105], 0
	v_mov_b64_e32 v[106:107], 0
	v_mov_b64_e32 v[108:109], 0
	v_mov_b64_e32 v[110:111], 0
	v_mov_b64_e32 v[112:113], 0
	v_mov_b64_e32 v[114:115], 0
	v_mov_b64_e32 v[116:117], 0
	v_mov_b64_e32 v[118:119], 0
	v_mov_b64_e32 v[120:121], 0
	v_mov_b64_e32 v[122:123], 0
	v_mov_b64_e32 v[124:125], 0
	v_mov_b64_e32 v[126:127], 0

.LBB0_424:
	s_ashr_i32 s37, s36, 31
	s_lshl_b64 s[0:1], s[36:37], 21
	s_add_u32 s38, s25, s0
	s_addc_u32 s39, s26, s1
	s_and_b64 s[0:1], s[2:3], exec
	s_cselect_b32 s49, s39, s47
	s_cselect_b32 s48, s38, s46
	s_ashr_i32 s35, s34, 31
	s_lshl_b64 s[0:1], s[34:35], 21
	s_add_u32 s40, s27, s0
	s_addc_u32 s41, s58, s1
	s_and_b64 s[0:1], s[2:3], exec
	v_mov_b32_e32 v0, 0
	s_cselect_b32 s51, s41, s45
	s_cselect_b32 s50, s40, s44
	s_mov_b32 s13, -2
	s_mov_b32 s35, 0
	v_mov_b64_e32 v[0:1], 0
	v_mov_b64_e32 v[2:3], 0
	v_mov_b64_e32 v[4:5], 0
	v_mov_b64_e32 v[6:7], 0
	v_mov_b64_e32 v[8:9], 0
	v_mov_b64_e32 v[10:11], 0
	v_mov_b64_e32 v[12:13], 0
	v_mov_b64_e32 v[14:15], 0
	v_mov_b64_e32 v[16:17], 0
	v_mov_b64_e32 v[18:19], 0
	v_mov_b64_e32 v[20:21], 0
	v_mov_b64_e32 v[22:23], 0
	v_mov_b64_e32 v[24:25], 0
	v_mov_b64_e32 v[26:27], 0
	v_mov_b64_e32 v[28:29], 0
	v_mov_b64_e32 v[30:31], 0
	v_mov_b64_e32 v[32:33], 0
	v_mov_b64_e32 v[34:35], 0
	v_mov_b64_e32 v[36:37], 0
	v_mov_b64_e32 v[38:39], 0
	v_mov_b64_e32 v[40:41], 0
	v_mov_b64_e32 v[42:43], 0
	v_mov_b64_e32 v[44:45], 0
	v_mov_b64_e32 v[46:47], 0
	v_mov_b64_e32 v[48:49], 0
	v_mov_b64_e32 v[50:51], 0
	v_mov_b64_e32 v[52:53], 0
	v_mov_b64_e32 v[54:55], 0
	v_mov_b64_e32 v[56:57], 0
	v_mov_b64_e32 v[58:59], 0
	v_mov_b64_e32 v[60:61], 0
	v_mov_b64_e32 v[62:63], 0
	v_mov_b64_e32 v[64:65], 0
	v_mov_b64_e32 v[66:67], 0
	v_mov_b64_e32 v[68:69], 0
	v_mov_b64_e32 v[70:71], 0
	v_mov_b64_e32 v[72:73], 0
	v_mov_b64_e32 v[74:75], 0
	v_mov_b64_e32 v[76:77], 0
	v_mov_b64_e32 v[78:79], 0
	v_mov_b64_e32 v[80:81], 0
	v_mov_b64_e32 v[82:83], 0
	v_mov_b64_e32 v[84:85], 0
	v_mov_b64_e32 v[86:87], 0
	v_mov_b64_e32 v[88:89], 0
	v_mov_b64_e32 v[90:91], 0
	v_mov_b64_e32 v[92:93], 0
	v_mov_b64_e32 v[94:95], 0
	v_mov_b64_e32 v[96:97], 0
	v_mov_b64_e32 v[98:99], 0
	v_mov_b64_e32 v[100:101], 0
	v_mov_b64_e32 v[102:103], 0
	v_mov_b64_e32 v[104:105], 0
	v_mov_b64_e32 v[106:107], 0
	v_mov_b64_e32 v[108:109], 0
	v_mov_b64_e32 v[110:111], 0
	v_mov_b64_e32 v[112:113], 0
	v_mov_b64_e32 v[114:115], 0
	v_mov_b64_e32 v[116:117], 0
	v_mov_b64_e32 v[118:119], 0
	v_mov_b64_e32 v[120:121], 0
	v_mov_b64_e32 v[122:123], 0
	v_mov_b64_e32 v[124:125], 0
	v_mov_b64_e32 v[126:127], 0
	s_branch .LBB0_426

.LBB0_676:
	s_ashr_i32 s17, s16, 31
	s_lshl_b64 s[0:1], s[16:17], 21
	s_add_u32 s18, s25, s0
	s_addc_u32 s19, s26, s1
	s_and_b64 s[0:1], s[2:3], exec
	s_cselect_b32 s56, s19, s37
	s_cselect_b32 s57, s18, s36
	s_ashr_i32 s15, s14, 31
	s_lshl_b64 s[0:1], s[14:15], 21
	s_add_u32 s20, s27, s0
	s_addc_u32 s21, s42, s1
	s_and_b64 s[0:1], s[2:3], exec
	s_cselect_b32 s15, s21, s39
	s_cselect_b32 s58, s20, s38
	s_add_u32 s36, s36, 0x100080
	s_addc_u32 s37, s37, 0
	s_add_u32 s59, s38, 0x100
	v_mov_b32_e32 v0, 0
	s_addc_u32 s60, s39, 0
	s_mov_b32 s61, -2
	v_mov_b64_e32 v[0:1], 0
	v_mov_b64_e32 v[2:3], 0
	v_mov_b64_e32 v[4:5], 0
	v_mov_b64_e32 v[6:7], 0
	v_mov_b64_e32 v[8:9], 0
	v_mov_b64_e32 v[10:11], 0
	v_mov_b64_e32 v[12:13], 0
	v_mov_b64_e32 v[14:15], 0
	v_mov_b64_e32 v[16:17], 0
	v_mov_b64_e32 v[18:19], 0
	v_mov_b64_e32 v[20:21], 0
	v_mov_b64_e32 v[22:23], 0
	v_mov_b64_e32 v[24:25], 0
	v_mov_b64_e32 v[26:27], 0
	v_mov_b64_e32 v[28:29], 0
	v_mov_b64_e32 v[30:31], 0
	v_mov_b64_e32 v[32:33], 0
	v_mov_b64_e32 v[34:35], 0
	v_mov_b64_e32 v[36:37], 0
	v_mov_b64_e32 v[38:39], 0
	v_mov_b64_e32 v[40:41], 0
	v_mov_b64_e32 v[42:43], 0
	v_mov_b64_e32 v[44:45], 0
	v_mov_b64_e32 v[46:47], 0
	v_mov_b64_e32 v[48:49], 0
	v_mov_b64_e32 v[50:51], 0
	v_mov_b64_e32 v[52:53], 0
	v_mov_b64_e32 v[54:55], 0
	v_mov_b64_e32 v[56:57], 0
	v_mov_b64_e32 v[58:59], 0
	v_mov_b64_e32 v[60:61], 0
	v_mov_b64_e32 v[62:63], 0
	v_mov_b64_e32 v[64:65], 0
	v_mov_b64_e32 v[66:67], 0
	v_mov_b64_e32 v[68:69], 0
	v_mov_b64_e32 v[70:71], 0
	v_mov_b64_e32 v[72:73], 0
	v_mov_b64_e32 v[74:75], 0
	v_mov_b64_e32 v[76:77], 0
	v_mov_b64_e32 v[78:79], 0
	v_mov_b64_e32 v[80:81], 0
	v_mov_b64_e32 v[82:83], 0
	v_mov_b64_e32 v[84:85], 0
	v_mov_b64_e32 v[86:87], 0
	v_mov_b64_e32 v[88:89], 0
	v_mov_b64_e32 v[90:91], 0
	v_mov_b64_e32 v[92:93], 0
	v_mov_b64_e32 v[94:95], 0
	v_mov_b64_e32 v[96:97], 0
	v_mov_b64_e32 v[98:99], 0
	v_mov_b64_e32 v[100:101], 0
	v_mov_b64_e32 v[102:103], 0
	v_mov_b64_e32 v[104:105], 0
	v_mov_b64_e32 v[106:107], 0
	v_mov_b64_e32 v[108:109], 0
	v_mov_b64_e32 v[110:111], 0
	v_mov_b64_e32 v[112:113], 0
	v_mov_b64_e32 v[114:115], 0
	v_mov_b64_e32 v[116:117], 0
	v_mov_b64_e32 v[118:119], 0
	v_mov_b64_e32 v[120:121], 0
	v_mov_b64_e32 v[122:123], 0
	v_mov_b64_e32 v[124:125], 0
	v_mov_b64_e32 v[126:127], 0

.LBB0_704:
	s_ashr_i32 s35, s34, 31
	s_lshl_b64 s[0:1], s[34:35], 20
	s_add_u32 s36, s25, s0
	s_addc_u32 s37, s26, s1
	s_and_b64 s[0:1], s[2:3], exec
	s_cselect_b32 s60, s37, s45
	s_cselect_b32 s66, s36, s44
	s_ashr_i32 s31, s30, 31
	s_lshl_b64 s[0:1], s[30:31], 20
	s_add_u32 s38, s27, s0
	s_addc_u32 s39, s50, s1
	s_and_b64 s[0:1], s[2:3], exec
	s_cselect_b32 s31, s39, s47
	s_cselect_b32 s67, s38, s46
	s_add_u32 s44, s44, 0x80080
	s_addc_u32 s45, s45, 0
	s_add_u32 s68, s46, 0x100
	v_mov_b32_e32 v32, 0
	s_addc_u32 s69, s47, 0
	s_mov_b32 s70, -2
	v_mov_b64_e32 v[32:33], 0
	v_mov_b64_e32 v[34:35], 0
	v_mov_b64_e32 v[36:37], 0
	v_mov_b64_e32 v[38:39], 0
	v_mov_b64_e32 v[40:41], 0
	v_mov_b64_e32 v[42:43], 0
	v_mov_b64_e32 v[44:45], 0
	v_mov_b64_e32 v[46:47], 0
	v_mov_b64_e32 v[48:49], 0
	v_mov_b64_e32 v[50:51], 0
	v_mov_b64_e32 v[52:53], 0
	v_mov_b64_e32 v[54:55], 0
	v_mov_b64_e32 v[56:57], 0
	v_mov_b64_e32 v[58:59], 0
	v_mov_b64_e32 v[60:61], 0
	v_mov_b64_e32 v[62:63], 0
	v_mov_b64_e32 v[64:65], 0
	v_mov_b64_e32 v[66:67], 0
	v_mov_b64_e32 v[68:69], 0
	v_mov_b64_e32 v[70:71], 0
	v_mov_b64_e32 v[72:73], 0
	v_mov_b64_e32 v[74:75], 0
	v_mov_b64_e32 v[76:77], 0
	v_mov_b64_e32 v[78:79], 0
	v_mov_b64_e32 v[80:81], 0
	v_mov_b64_e32 v[82:83], 0
	v_mov_b64_e32 v[84:85], 0
	v_mov_b64_e32 v[86:87], 0
	v_mov_b64_e32 v[88:89], 0
	v_mov_b64_e32 v[90:91], 0
	v_mov_b64_e32 v[92:93], 0
	v_mov_b64_e32 v[94:95], 0
	v_mov_b64_e32 v[96:97], 0
	v_mov_b64_e32 v[98:99], 0
	v_mov_b64_e32 v[100:101], 0
	v_mov_b64_e32 v[102:103], 0
	v_mov_b64_e32 v[104:105], 0
	v_mov_b64_e32 v[106:107], 0
	v_mov_b64_e32 v[108:109], 0
	v_mov_b64_e32 v[110:111], 0
	v_mov_b64_e32 v[112:113], 0
	v_mov_b64_e32 v[114:115], 0
	v_mov_b64_e32 v[116:117], 0
	v_mov_b64_e32 v[118:119], 0
	v_mov_b64_e32 v[120:121], 0
	v_mov_b64_e32 v[122:123], 0
	v_mov_b64_e32 v[124:125], 0
	v_mov_b64_e32 v[126:127], 0
	v_mov_b64_e32 v[128:129], 0
	v_mov_b64_e32 v[130:131], 0
	v_mov_b64_e32 v[132:133], 0
	v_mov_b64_e32 v[134:135], 0
	v_mov_b64_e32 v[136:137], 0
	v_mov_b64_e32 v[138:139], 0
	v_mov_b64_e32 v[140:141], 0
	v_mov_b64_e32 v[142:143], 0
	v_mov_b64_e32 v[144:145], 0
	v_mov_b64_e32 v[146:147], 0
	v_mov_b64_e32 v[148:149], 0
	v_mov_b64_e32 v[150:151], 0
	v_mov_b64_e32 v[152:153], 0
	v_mov_b64_e32 v[154:155], 0
	v_mov_b64_e32 v[156:157], 0
	v_mov_b64_e32 v[158:159], 0

.LBB0_1636:
	s_ashr_i32 s35, s34, 31
	s_lshl_b64 s[0:1], s[34:35], 21
	s_add_u32 s36, s25, s0
	s_addc_u32 s37, s26, s1
	s_and_b64 s[0:1], s[4:5], exec
	s_cselect_b32 s35, s37, s43
	s_cselect_b32 s64, s36, s42
	s_ashr_i32 s31, s30, 31
	s_lshl_b64 s[0:1], s[30:31], 21
	s_add_u32 s38, s27, s0
	s_addc_u32 s39, s48, s1
	s_and_b64 s[0:1], s[4:5], exec
	s_cselect_b32 s31, s39, s45
	s_cselect_b32 s65, s38, s44
	s_add_u32 s42, s42, 0x100080
	s_addc_u32 s43, s43, 0
	s_add_u32 s66, s44, 0x100
	v_mov_b32_e32 v0, 0
	s_addc_u32 s67, s45, 0
	s_mov_b32 s68, -2
	v_mov_b64_e32 v[0:1], 0
	v_mov_b64_e32 v[2:3], 0
	v_mov_b64_e32 v[4:5], 0
	v_mov_b64_e32 v[6:7], 0
	v_mov_b64_e32 v[8:9], 0
	v_mov_b64_e32 v[10:11], 0
	v_mov_b64_e32 v[12:13], 0
	v_mov_b64_e32 v[14:15], 0
	v_mov_b64_e32 v[16:17], 0
	v_mov_b64_e32 v[18:19], 0
	v_mov_b64_e32 v[20:21], 0
	v_mov_b64_e32 v[22:23], 0
	v_mov_b64_e32 v[24:25], 0
	v_mov_b64_e32 v[26:27], 0
	v_mov_b64_e32 v[28:29], 0
	v_mov_b64_e32 v[30:31], 0
	v_mov_b64_e32 v[32:33], 0
	v_mov_b64_e32 v[34:35], 0
	v_mov_b64_e32 v[36:37], 0
	v_mov_b64_e32 v[38:39], 0
	v_mov_b64_e32 v[40:41], 0
	v_mov_b64_e32 v[42:43], 0
	v_mov_b64_e32 v[44:45], 0
	v_mov_b64_e32 v[46:47], 0
	v_mov_b64_e32 v[48:49], 0
	v_mov_b64_e32 v[50:51], 0
	v_mov_b64_e32 v[52:53], 0
	v_mov_b64_e32 v[54:55], 0
	v_mov_b64_e32 v[56:57], 0
	v_mov_b64_e32 v[58:59], 0
	v_mov_b64_e32 v[60:61], 0
	v_mov_b64_e32 v[62:63], 0
	v_mov_b64_e32 v[64:65], 0
	v_mov_b64_e32 v[66:67], 0
	v_mov_b64_e32 v[68:69], 0
	v_mov_b64_e32 v[70:71], 0
	v_mov_b64_e32 v[72:73], 0
	v_mov_b64_e32 v[74:75], 0
	v_mov_b64_e32 v[76:77], 0
	v_mov_b64_e32 v[78:79], 0
	v_mov_b64_e32 v[80:81], 0
	v_mov_b64_e32 v[82:83], 0
	v_mov_b64_e32 v[84:85], 0
	v_mov_b64_e32 v[86:87], 0
	v_mov_b64_e32 v[88:89], 0
	v_mov_b64_e32 v[90:91], 0
	v_mov_b64_e32 v[92:93], 0
	v_mov_b64_e32 v[94:95], 0
	v_mov_b64_e32 v[96:97], 0
	v_mov_b64_e32 v[98:99], 0
	v_mov_b64_e32 v[100:101], 0
	v_mov_b64_e32 v[102:103], 0
	v_mov_b64_e32 v[104:105], 0
	v_mov_b64_e32 v[106:107], 0
	v_mov_b64_e32 v[108:109], 0
	v_mov_b64_e32 v[110:111], 0
	v_mov_b64_e32 v[112:113], 0
	v_mov_b64_e32 v[114:115], 0
	v_mov_b64_e32 v[116:117], 0
	v_mov_b64_e32 v[118:119], 0
	v_mov_b64_e32 v[120:121], 0
	v_mov_b64_e32 v[122:123], 0
	v_mov_b64_e32 v[124:125], 0
	v_mov_b64_e32 v[126:127], 0

.LBB0_1812:
	s_ashr_i32 s19, s18, 31
	s_lshl_b64 s[0:1], s[18:19], 21
	s_add_u32 s20, s25, s0
	s_addc_u32 s21, s26, s1
	s_and_b64 s[0:1], s[6:7], exec
	s_cselect_b32 s59, s21, s37
	s_cselect_b32 s60, s20, s36
	s_ashr_i32 s17, s16, 31
	s_lshl_b64 s[0:1], s[16:17], 21
	s_add_u32 s28, s27, s0
	s_addc_u32 s29, s42, s1
	s_and_b64 s[0:1], s[6:7], exec
	s_cselect_b32 s17, s29, s39
	s_cselect_b32 s61, s28, s38
	s_add_u32 s36, s36, 0x100080
	s_addc_u32 s37, s37, 0
	s_add_u32 s62, s38, 0x100
	v_mov_b32_e32 v0, 0
	s_addc_u32 s63, s39, 0
	s_mov_b32 s64, -2
	v_mov_b64_e32 v[0:1], 0
	v_mov_b64_e32 v[2:3], 0
	v_mov_b64_e32 v[4:5], 0
	v_mov_b64_e32 v[6:7], 0
	v_mov_b64_e32 v[8:9], 0
	v_mov_b64_e32 v[10:11], 0
	v_mov_b64_e32 v[12:13], 0
	v_mov_b64_e32 v[14:15], 0
	v_mov_b64_e32 v[16:17], 0
	v_mov_b64_e32 v[18:19], 0
	v_mov_b64_e32 v[20:21], 0
	v_mov_b64_e32 v[22:23], 0
	v_mov_b64_e32 v[24:25], 0
	v_mov_b64_e32 v[26:27], 0
	v_mov_b64_e32 v[28:29], 0
	v_mov_b64_e32 v[30:31], 0
	v_mov_b64_e32 v[32:33], 0
	v_mov_b64_e32 v[34:35], 0
	v_mov_b64_e32 v[36:37], 0
	v_mov_b64_e32 v[38:39], 0
	v_mov_b64_e32 v[40:41], 0
	v_mov_b64_e32 v[42:43], 0
	v_mov_b64_e32 v[44:45], 0
	v_mov_b64_e32 v[46:47], 0
	v_mov_b64_e32 v[48:49], 0
	v_mov_b64_e32 v[50:51], 0
	v_mov_b64_e32 v[52:53], 0
	v_mov_b64_e32 v[54:55], 0
	v_mov_b64_e32 v[56:57], 0
	v_mov_b64_e32 v[58:59], 0
	v_mov_b64_e32 v[60:61], 0
	v_mov_b64_e32 v[62:63], 0
	v_mov_b64_e32 v[64:65], 0
	v_mov_b64_e32 v[66:67], 0
	v_mov_b64_e32 v[68:69], 0
	v_mov_b64_e32 v[70:71], 0
	v_mov_b64_e32 v[72:73], 0
	v_mov_b64_e32 v[74:75], 0
	v_mov_b64_e32 v[76:77], 0
	v_mov_b64_e32 v[78:79], 0
	v_mov_b64_e32 v[80:81], 0
	v_mov_b64_e32 v[82:83], 0
	v_mov_b64_e32 v[84:85], 0
	v_mov_b64_e32 v[86:87], 0
	v_mov_b64_e32 v[88:89], 0
	v_mov_b64_e32 v[90:91], 0
	v_mov_b64_e32 v[92:93], 0
	v_mov_b64_e32 v[94:95], 0
	v_mov_b64_e32 v[96:97], 0
	v_mov_b64_e32 v[98:99], 0
	v_mov_b64_e32 v[100:101], 0
	v_mov_b64_e32 v[102:103], 0
	v_mov_b64_e32 v[104:105], 0
	v_mov_b64_e32 v[106:107], 0
	v_mov_b64_e32 v[108:109], 0
	v_mov_b64_e32 v[110:111], 0
	v_mov_b64_e32 v[112:113], 0
	v_mov_b64_e32 v[114:115], 0
	v_mov_b64_e32 v[116:117], 0
	v_mov_b64_e32 v[118:119], 0
	v_mov_b64_e32 v[120:121], 0
	v_mov_b64_e32 v[122:123], 0
	v_mov_b64_e32 v[124:125], 0
	v_mov_b64_e32 v[126:127], 0

.LBB0_1832:
	s_ashr_i32 s19, s18, 31
	s_lshl_b64 s[0:1], s[18:19], 20
	s_add_u32 s20, s25, s0
	s_addc_u32 s21, s42, s1
	s_and_b64 s[0:1], s[6:7], exec
	s_cselect_b32 s26, s21, s37
	s_cselect_b32 s27, s20, s36
	s_ashr_i32 s17, s16, 31
	s_lshl_b64 s[0:1], s[16:17], 20
	s_add_u32 s28, s43, s0
	s_addc_u32 s29, s44, s1
	s_and_b64 s[0:1], s[6:7], exec
	s_cselect_b32 s17, s29, s39
	s_cselect_b32 s31, s28, s38
	s_add_u32 s36, s36, 0x80080
	s_addc_u32 s37, s37, 0
	s_add_u32 s63, s38, 0x100
	v_mov_b32_e32 v32, 0
	s_addc_u32 s64, s39, 0
	s_mov_b32 s65, -2
	v_mov_b64_e32 v[32:33], 0
	v_mov_b64_e32 v[34:35], 0
	v_mov_b64_e32 v[36:37], 0
	v_mov_b64_e32 v[38:39], 0
	v_mov_b64_e32 v[40:41], 0
	v_mov_b64_e32 v[42:43], 0
	v_mov_b64_e32 v[44:45], 0
	v_mov_b64_e32 v[46:47], 0
	v_mov_b64_e32 v[48:49], 0
	v_mov_b64_e32 v[50:51], 0
	v_mov_b64_e32 v[52:53], 0
	v_mov_b64_e32 v[54:55], 0
	v_mov_b64_e32 v[56:57], 0
	v_mov_b64_e32 v[58:59], 0
	v_mov_b64_e32 v[60:61], 0
	v_mov_b64_e32 v[62:63], 0
	v_mov_b64_e32 v[64:65], 0
	v_mov_b64_e32 v[66:67], 0
	v_mov_b64_e32 v[68:69], 0
	v_mov_b64_e32 v[70:71], 0
	v_mov_b64_e32 v[72:73], 0
	v_mov_b64_e32 v[74:75], 0
	v_mov_b64_e32 v[76:77], 0
	v_mov_b64_e32 v[78:79], 0
	v_mov_b64_e32 v[80:81], 0
	v_mov_b64_e32 v[82:83], 0
	v_mov_b64_e32 v[84:85], 0
	v_mov_b64_e32 v[86:87], 0
	v_mov_b64_e32 v[88:89], 0
	v_mov_b64_e32 v[90:91], 0
	v_mov_b64_e32 v[92:93], 0
	v_mov_b64_e32 v[94:95], 0
	v_mov_b64_e32 v[96:97], 0
	v_mov_b64_e32 v[98:99], 0
	v_mov_b64_e32 v[100:101], 0
	v_mov_b64_e32 v[102:103], 0
	v_mov_b64_e32 v[104:105], 0
	v_mov_b64_e32 v[106:107], 0
	v_mov_b64_e32 v[108:109], 0
	v_mov_b64_e32 v[110:111], 0
	v_mov_b64_e32 v[112:113], 0
	v_mov_b64_e32 v[114:115], 0
	v_mov_b64_e32 v[116:117], 0
	v_mov_b64_e32 v[118:119], 0
	v_mov_b64_e32 v[120:121], 0
	v_mov_b64_e32 v[122:123], 0
	v_mov_b64_e32 v[124:125], 0
	v_mov_b64_e32 v[126:127], 0
	v_mov_b64_e32 v[128:129], 0
	v_mov_b64_e32 v[130:131], 0
	v_mov_b64_e32 v[132:133], 0
	v_mov_b64_e32 v[134:135], 0
	v_mov_b64_e32 v[136:137], 0
	v_mov_b64_e32 v[138:139], 0
	v_mov_b64_e32 v[140:141], 0
	v_mov_b64_e32 v[142:143], 0
	v_mov_b64_e32 v[144:145], 0
	v_mov_b64_e32 v[146:147], 0
	v_mov_b64_e32 v[148:149], 0
	v_mov_b64_e32 v[150:151], 0
	v_mov_b64_e32 v[152:153], 0
	v_mov_b64_e32 v[154:155], 0
	v_mov_b64_e32 v[156:157], 0
	v_mov_b64_e32 v[158:159], 0

.LBB0_1973:
	s_ashr_i32 s37, s36, 31
	s_lshl_b64 s[0:1], s[36:37], 20
	s_add_u32 s38, s23, s0
	s_addc_u32 s39, s25, s1
	s_and_b64 s[0:1], s[2:3], exec
	s_cselect_b32 s49, s39, s47
	s_cselect_b32 s48, s38, s46
	s_ashr_i32 s35, s34, 31
	s_lshl_b64 s[0:1], s[34:35], 20
	s_add_u32 s40, s26, s0
	s_addc_u32 s41, s27, s1
	s_and_b64 s[0:1], s[2:3], exec
	v_mov_b32_e32 v32, 0
	s_cselect_b32 s51, s41, s45
	s_cselect_b32 s50, s40, s44
	s_mov_b32 s35, -2
	s_mov_b32 s37, 0
	v_mov_b64_e32 v[32:33], 0
	v_mov_b64_e32 v[34:35], 0
	v_mov_b64_e32 v[36:37], 0
	v_mov_b64_e32 v[38:39], 0
	v_mov_b64_e32 v[40:41], 0
	v_mov_b64_e32 v[42:43], 0
	v_mov_b64_e32 v[44:45], 0
	v_mov_b64_e32 v[46:47], 0
	v_mov_b64_e32 v[48:49], 0
	v_mov_b64_e32 v[50:51], 0
	v_mov_b64_e32 v[52:53], 0
	v_mov_b64_e32 v[54:55], 0
	v_mov_b64_e32 v[56:57], 0
	v_mov_b64_e32 v[58:59], 0
	v_mov_b64_e32 v[60:61], 0
	v_mov_b64_e32 v[62:63], 0
	v_mov_b64_e32 v[64:65], 0
	v_mov_b64_e32 v[66:67], 0
	v_mov_b64_e32 v[68:69], 0
	v_mov_b64_e32 v[70:71], 0
	v_mov_b64_e32 v[72:73], 0
	v_mov_b64_e32 v[74:75], 0
	v_mov_b64_e32 v[76:77], 0
	v_mov_b64_e32 v[78:79], 0
	v_mov_b64_e32 v[80:81], 0
	v_mov_b64_e32 v[82:83], 0
	v_mov_b64_e32 v[84:85], 0
	v_mov_b64_e32 v[86:87], 0
	v_mov_b64_e32 v[88:89], 0
	v_mov_b64_e32 v[90:91], 0
	v_mov_b64_e32 v[92:93], 0
	v_mov_b64_e32 v[94:95], 0
	v_mov_b64_e32 v[96:97], 0
	v_mov_b64_e32 v[98:99], 0
	v_mov_b64_e32 v[100:101], 0
	v_mov_b64_e32 v[102:103], 0
	v_mov_b64_e32 v[104:105], 0
	v_mov_b64_e32 v[106:107], 0
	v_mov_b64_e32 v[108:109], 0
	v_mov_b64_e32 v[110:111], 0
	v_mov_b64_e32 v[112:113], 0
	v_mov_b64_e32 v[114:115], 0
	v_mov_b64_e32 v[116:117], 0
	v_mov_b64_e32 v[118:119], 0
	v_mov_b64_e32 v[120:121], 0
	v_mov_b64_e32 v[122:123], 0
	v_mov_b64_e32 v[124:125], 0
	v_mov_b64_e32 v[126:127], 0
	v_mov_b64_e32 v[128:129], 0
	v_mov_b64_e32 v[130:131], 0
	v_mov_b64_e32 v[132:133], 0
	v_mov_b64_e32 v[134:135], 0
	v_mov_b64_e32 v[136:137], 0
	v_mov_b64_e32 v[138:139], 0
	v_mov_b64_e32 v[140:141], 0
	v_mov_b64_e32 v[142:143], 0
	v_mov_b64_e32 v[144:145], 0
	v_mov_b64_e32 v[146:147], 0
	v_mov_b64_e32 v[148:149], 0
	v_mov_b64_e32 v[150:151], 0
	v_mov_b64_e32 v[152:153], 0
	v_mov_b64_e32 v[154:155], 0
	v_mov_b64_e32 v[156:157], 0
	v_mov_b64_e32 v[158:159], 0
	s_branch .LBB0_1975
